# P8 tail task processes two rows per trip with both rows' loads in flight
# speedup vs baseline: 1.0582x; 1.0026x over previous
.LBB0_1243:
.LBB0_1244:
	s_add_i32 s16, s47, s48
	s_cmpk_gt_u32 s16, 0xffff
	s_mov_b64 s[30:31], -1
	s_cbranch_scc0 .LBB0_1246
	s_add_i32 s34, s16, 0xffff0000
	s_lshr_b32 s11, s34, 5
	s_and_b32 s10, s16, 31
	s_mul_hi_u32 s28, s11, 0x840
	s_mulk_i32 s11, 0x840
	s_or_b32 s49, s10, 0x800
	s_or_b32 s10, s11, s10
	s_add_u32 s10, s10, 0x10800
	s_mov_b32 s35, s17
	s_addc_u32 s11, s28, 0
	s_lshl_b64 s[28:29], s[34:35], 7
	s_mov_b64 s[30:31], 0

.LBB0_1251:
	s_or_b64 exec, exec, s[40:41]
	s_add_u32 s36, s8, s36
	s_addc_u32 s37, s9, s37
	s_lshl_b64 s[34:35], s[34:35], 10
	s_add_u32 s34, s36, s34
	s_addc_u32 s35, s37, s35
	s_lshl_b64 s[36:37], s[16:17], 2
	s_add_u32 s36, s42, s36
	s_addc_u32 s37, s43, s37
	global_load_dword v35, v1, s[36:37]
	s_add_i32 s50, s47, s48
	s_add_i32 s50, s50, 8
	s_mov_b32 s51, s17
	s_cmpk_gt_u32 s50, 0xffff
	s_mov_b64 s[60:61], -1
	s_cbranch_scc0 .Lt2b_1246
	s_add_i32 s56, s50, 0xffff0000
	s_lshr_b32 s55, s56, 5
	s_and_b32 s54, s50, 31
	s_mul_hi_u32 s58, s55, 0x840
	s_mulk_i32 s55, 0x840
	s_or_b32 s52, s54, 0x800
	s_or_b32 s54, s55, s54
	s_add_u32 s54, s54, 0x10800
	s_mov_b32 s57, s51
	s_addc_u32 s55, s58, 0
	s_lshl_b64 s[58:59], s[56:57], 7
	s_mov_b64 s[60:61], 0
.Lt2b_1246:
	s_andn2_b64 vcc, exec, s[60:61]
	s_lshl_b64 s[64:65], s[50:51], 7
	s_cbranch_vccnz .Lt2b_1248
	s_and_b32 s52, s50, 0x7ff
	s_mov_b64 s[62:63], 0x18300000
	s_mov_b64 s[60:61], 0x1c300000
	s_mov_b64 s[58:59], s[64:65]
	s_mov_b64 s[56:57], s[50:51]
	s_mov_b64 s[54:55], s[50:51]
	s_branch .Lt2b_1249
.Lt2b_1248:
	s_mov_b64 s[62:63], 0x1cb00000
	s_mov_b64 s[60:61], 0x1cb40000
.Lt2b_1249:
	s_lshl_b64 s[68:69], s[54:55], 9
	s_waitcnt lgkmcnt(0)
	v_lshl_add_u64 v[46:47], v[2:3], 0, s[68:69]
	global_load_dwordx2 v[46:47], v[46:47], off
	v_mov_b32_e32 v0, 0
	v_mov_b32_e32 v48, 0
	v_mov_b32_e32 v49, 0
	s_and_saveexec_b64 s[68:69], s[4:5]
	s_cbranch_execz .Lt2b_1251
	v_lshl_add_u64 v[32:33], v[4:5], 0, s[64:65]
	global_load_dword v48, v[32:33], off
	global_load_dword v49, v[6:7], off
	v_lshl_or_b32 v42, s52, 5, v12
	v_mov_b32_e32 v43, 0
	v_lshl_add_u64 v[44:45], v[42:43], 2, s[18:19]
	global_load_dword v50, v[44:45], off offset:64
	global_load_dword v51, v[44:45], off
.Lt2b_1251:
	s_or_b64 exec, exec, s[68:69]
	s_add_u32 s62, s8, s62
	s_addc_u32 s63, s9, s63
	s_lshl_b64 s[56:57], s[56:57], 10
	s_add_u32 s56, s62, s56
	s_addc_u32 s57, s63, s57
	s_lshl_b64 s[62:63], s[50:51], 2
	s_add_u32 s62, s42, s62
	s_addc_u32 s63, s43, s63
	global_load_dword v52, v1, s[62:63]
	s_waitcnt vmcnt(10)
	v_mul_f32_e32 v36, v31, v31
	v_lshlrev_b32_e32 v34, 16, v11
	v_lshlrev_b32_e32 v32, 16, v10
	v_and_b32_e32 v33, 0xffff0000, v10
	v_add_f32_dpp v36, v36, v36 quad_perm:[1,0,3,2] row_mask:0xf bank_mask:0xf
	s_nop 1
	v_add_f32_dpp v36, v36, v36 quad_perm:[2,3,0,1] row_mask:0xf bank_mask:0xf
	s_nop 1
	v_add_f32_dpp v36, v36, v36 row_half_mirror row_mask:0xf bank_mask:0xf
	s_nop 1
	v_add_f32_dpp v36, v36, v36 row_mirror row_mask:0xf bank_mask:0xf
	ds_bpermute_b32 v37, v29, v36
	s_waitcnt lgkmcnt(0)
	v_add_f32_e32 v10, v36, v37
	s_waitcnt vmcnt(6)
	v_fmamk_f32 v35, v35, 0x3b800000, v14
	v_mul_f32_e32 v37, 0x4b800000, v35
	v_cmp_gt_f32_e32 vcc, s46, v35
	s_nop 1
	v_cndmask_b32_e32 v35, v35, v37, vcc
	v_rsq_f32_e32 v37, v35
	v_and_b32_e32 v35, 0xffff0000, v11
	v_mul_f32_e32 v36, 0x45800000, v37
	v_cndmask_b32_e32 v36, v37, v36, vcc
	v_pk_mul_f32 v[34:35], v[36:37], v[34:35] op_sel_hi:[0,1]
	v_pk_mul_f32 v[32:33], v[36:37], v[32:33] op_sel_hi:[0,1]
	global_store_dwordx4 v15, v[32:35], s[34:35] nt
	v_fmamk_f32 v10, v10, 0x3d000000, v14
	v_mul_f32_e32 v11, 0x4b800000, v10
	v_cmp_gt_f32_e32 vcc, s46, v10
	s_nop 1
	v_cndmask_b32_e32 v10, v10, v11, vcc
	v_rsq_f32_e32 v10, v10
	s_nop 0
	v_mul_f32_e32 v11, 0x45800000, v10
	v_cndmask_b32_e32 v10, v10, v11, vcc
	v_mul_f32_e32 v10, v31, v10
	s_waitcnt vmcnt(7)
	v_mul_f32_e32 v10, v10, v38
	ds_bpermute_b32 v11, v29, v10
	s_and_saveexec_b64 s[34:35], s[4:5]
	s_cbranch_execz .Lt2_aend
	s_add_u32 s16, s8, s30
	s_addc_u32 s30, s9, s31
	s_add_u32 s28, s16, s28
	s_addc_u32 s29, s30, s29
	s_lshl_b64 s[10:11], s[10:11], 6
	s_waitcnt vmcnt(7) lgkmcnt(0)
	v_mul_f32_e32 v0, v39, v11
	v_cndmask_b32_e64 v0, v0, -v0, s[6:7]
	s_waitcnt vmcnt(7)
	v_fmac_f32_e32 v0, v10, v40
	global_store_dword v16, v0, s[28:29]
	v_cvt_pk_bf16_f32 v0, v0, s0
	v_lshl_add_u64 v[10:11], v[8:9], 0, s[10:11]
	global_store_short v[10:11], v0, off
.Lt2_aend:
	s_or_b64 exec, exec, s[34:35]
	s_waitcnt vmcnt(7)
	v_mul_f32_e32 v36, v48, v48
	v_lshlrev_b32_e32 v34, 16, v47
	v_lshlrev_b32_e32 v32, 16, v46
	v_and_b32_e32 v33, 0xffff0000, v46
	v_add_f32_dpp v36, v36, v36 quad_perm:[1,0,3,2] row_mask:0xf bank_mask:0xf
	s_nop 1
	v_add_f32_dpp v36, v36, v36 quad_perm:[2,3,0,1] row_mask:0xf bank_mask:0xf
	s_nop 1
	v_add_f32_dpp v36, v36, v36 row_half_mirror row_mask:0xf bank_mask:0xf
	s_nop 1
	v_add_f32_dpp v36, v36, v36 row_mirror row_mask:0xf bank_mask:0xf
	ds_bpermute_b32 v37, v29, v36
	s_waitcnt lgkmcnt(0)
	v_add_f32_e32 v46, v36, v37
	s_waitcnt vmcnt(3)
	v_fmamk_f32 v35, v52, 0x3b800000, v14
	v_mul_f32_e32 v37, 0x4b800000, v35
	v_cmp_gt_f32_e32 vcc, s46, v35
	s_nop 1
	v_cndmask_b32_e32 v35, v35, v37, vcc
	v_rsq_f32_e32 v37, v35
	v_and_b32_e32 v35, 0xffff0000, v47
	v_mul_f32_e32 v36, 0x45800000, v37
	v_cndmask_b32_e32 v36, v37, v36, vcc
	v_pk_mul_f32 v[34:35], v[36:37], v[34:35] op_sel_hi:[0,1]
	v_pk_mul_f32 v[32:33], v[36:37], v[32:33] op_sel_hi:[0,1]
	global_store_dwordx4 v15, v[32:35], s[56:57] nt
	v_fmamk_f32 v46, v46, 0x3d000000, v14
	v_mul_f32_e32 v47, 0x4b800000, v46
	v_cmp_gt_f32_e32 vcc, s46, v46
	s_nop 1
	v_cndmask_b32_e32 v46, v46, v47, vcc
	v_rsq_f32_e32 v46, v46
	s_nop 0
	v_mul_f32_e32 v47, 0x45800000, v46
	v_cndmask_b32_e32 v46, v46, v47, vcc
	v_mul_f32_e32 v46, v48, v46
	s_waitcnt vmcnt(4)
	v_mul_f32_e32 v46, v46, v49
	ds_bpermute_b32 v47, v29, v46
	s_and_saveexec_b64 s[56:57], s[4:5]
	s_cbranch_execz .Lt2_bend
	s_add_u32 s50, s8, s60
	s_addc_u32 s60, s9, s61
	s_add_u32 s58, s50, s58
	s_addc_u32 s59, s60, s59
	s_lshl_b64 s[54:55], s[54:55], 6
	s_waitcnt vmcnt(4) lgkmcnt(0)
	v_mul_f32_e32 v0, v50, v47
	v_cndmask_b32_e64 v0, v0, -v0, s[6:7]
	s_waitcnt vmcnt(4)
	v_fmac_f32_e32 v0, v46, v51
	global_store_dword v16, v0, s[58:59]
	v_cvt_pk_bf16_f32 v0, v0, s0
	v_lshl_add_u64 v[46:47], v[8:9], 0, s[54:55]
	global_store_short v[46:47], v0, off
.Lt2_bend:
	s_or_b64 exec, exec, s[56:57]
	s_add_i32 s48, s48, 16
	s_cmpk_eq_i32 s48, 0x80
	s_cbranch_scc1 .LBB0_1235
	s_branch .LBB0_1244
